# phase 5: nt hint on the residual x loads (read once)
# speedup vs baseline: 1.0121x; 1.0011x over previous
; #define PG8_STAGE(bufoff, gbase, voff) do { _Pragma("unroll") for (int _i = 0; _i < 2; ++_i) \
;         __builtin_amdgcn_global_load_lds((const unsigned*)((const char*)(gbase) + (voff)[_i]), (PG8_LAS unsigned*)(lds + (bufoff) + ldsw + _i * 8192), 16, 0, 0); } while (0)
; #define PG8_LDA(dst, b, h) do { _Pragma("unroll") for (int m = 0; m < 4; ++m) _Pragma("unroll") for (int k = 0; k < 2; ++k) dst[m][k] = *(const PG8_LAS bf16x8*)(lds + PG8_SA(b, h) + aoff + m * 2048 + k * 1024); } while (0)
; #define PG8_LDB(dst, b, h) do { _Pragma("unroll") for (int n = 0; n < 2; ++n) _Pragma("unroll") for (int k = 0; k < 2; ++k) dst[n][k] = *(const PG8_LAS bf16x8*)(lds + PG8_SB(b, h) + boff + n * 2048 + k * 1024); } while (0)
; #define PG8_MMA(ai, bj, At, Bt) do { __builtin_amdgcn_s_setprio(1); _Pragma("unroll") for (int m = 0; m < 4; ++m) _Pragma("unroll") for (int n = 0; n < 2; ++n) _Pragma("unroll") for (int k = 0; k < 2; ++k) \
;         acc[ai][bj][m][n] = __builtin_amdgcn_mfma_f32_16x16x32_bf16(Bt[n][k], At[m][k], acc[ai][bj][m][n], 0, 0, 0); __builtin_amdgcn_s_setprio(0); } while (0)
; #define PG8_WAIT_L(n) asm volatile("s_waitcnt lgkmcnt(" #n ")" ::: "memory")
; #define PG8_BAR __builtin_amdgcn_s_barrier()
; #define PG8_SCHED __builtin_amdgcn_sched_barrier(0)
; template <class Epi, class Sched>
; __device__ __forceinline__ void gemm_phase(PG8_LAS unsigned char* lds, const Gemm g, const Sched& S, const Epi& E) {
;     ...
;             PG8_LDB(B0, 0, 0); PG8_SCHED; PG8_LDA(At, 0, 0); PG8_STAGE(PG8_SA(1, 1), a1 + hstep, voffA);
;             PG8_WAIT_L(8); PG8_BAR; PG8_WAIT_L(0); PG8_MMA(0, 0, At, B0); PG8_BAR; PG8_SCHED;
;             PG8_LDB(B1, 0, 1); PG8_STAGE(PG8_SB(0, 0), b2, voffB);
;             PG8_BAR; PG8_WAIT_L(0); PG8_MMA(0, 1, At, B1); PG8_BAR;
;             PG8_LDA(At, 0, 1); PG8_STAGE(PG8_SA(0, 0), a2, voffA);
;             PG8_BAR; PG8_WAIT_L(0); PG8_MMA(1, 0, At, B0); PG8_BAR; PG8_SCHED;
.LBB0_750:
	ds_read_b128 v[138:141], v147
	ds_read_b128 v[164:167], v148
	ds_read_b128 v[168:171], v149
	ds_read_b128 v[172:175], v150
	s_add_u32 s30, s28, 0xfffc0080
	s_addc_u32 s31, s29, -1
	s_cmp_eq_u32 s64, 12
	s_cselect_b32 s35, s17, s31
	s_cselect_b32 s34, s25, s30
	s_cselect_b32 s31, s15, s63
	s_cselect_b32 s30, s61, s62
	s_mov_b32 m0, s59
	v_lshl_add_u64 v[142:143], s[28:29], 0, v[134:135]
	ds_read_b128 v[176:179], v145
	ds_read_b128 v[180:183], v145 offset:1024
	ds_read_b128 v[184:187], v145 offset:2048
	ds_read_b128 v[188:191], v145 offset:3072
	ds_read_b128 v[192:195], v145 offset:4096
	ds_read_b128 v[196:199], v145 offset:5120
	ds_read_b128 v[200:203], v145 offset:6144
	ds_read_b128 v[204:207], v145 offset:7168
	global_load_lds_dwordx4 v[142:143], off
	v_lshl_add_u64 v[142:143], s[28:29], 0, v[136:137]
	s_mov_b32 m0, s60
	s_nop 0
	global_load_lds_dwordx4 v[142:143], off
	s_waitcnt lgkmcnt(8)
	s_barrier
	s_waitcnt lgkmcnt(0)
	s_setprio 1
	s_waitcnt lgkmcnt(0)
	v_mfma_f32_16x16x32_bf16 v[126:129], v[138:141], v[176:179], v[126:129]
	v_mfma_f32_16x16x32_bf16 v[122:125], v[168:171], v[176:179], v[122:125]
	v_mfma_f32_16x16x32_bf16 v[110:113], v[138:141], v[184:187], v[110:113]
	v_mfma_f32_16x16x32_bf16 v[106:109], v[168:171], v[184:187], v[106:109]
	v_mfma_f32_16x16x32_bf16 v[94:97], v[138:141], v[192:195], v[94:97]
	v_mfma_f32_16x16x32_bf16 v[90:93], v[168:171], v[192:195], v[90:93]
	v_mfma_f32_16x16x32_bf16 v[78:81], v[138:141], v[200:203], v[78:81]
	v_mfma_f32_16x16x32_bf16 v[74:77], v[168:171], v[200:203], v[74:77]
	v_mfma_f32_16x16x32_bf16 v[126:129], v[164:167], v[180:183], v[126:129]
	v_mfma_f32_16x16x32_bf16 v[122:125], v[172:175], v[180:183], v[122:125]
	v_mfma_f32_16x16x32_bf16 v[110:113], v[164:167], v[188:191], v[110:113]
	v_mfma_f32_16x16x32_bf16 v[106:109], v[172:175], v[188:191], v[106:109]
	v_mfma_f32_16x16x32_bf16 v[94:97], v[164:167], v[196:199], v[94:97]
	v_mfma_f32_16x16x32_bf16 v[90:93], v[172:175], v[196:199], v[90:93]
	v_mfma_f32_16x16x32_bf16 v[78:81], v[164:167], v[204:207], v[78:81]
	v_mfma_f32_16x16x32_bf16 v[74:77], v[172:175], v[204:207], v[74:77]
	s_setprio 0
	s_barrier
	s_mov_b32 m0, s27
	v_lshl_add_u64 v[142:143], s[30:31], 0, v[130:131]
	ds_read_b128 v[208:211], v151
	ds_read_b128 v[212:215], v152
	ds_read_b128 v[216:219], v153
	ds_read_b128 v[220:223], v154
	global_load_lds_dwordx4 v[142:143], off
	v_lshl_add_u64 v[224:225], s[30:31], 0, v[132:133]
	s_mov_b32 m0, s41
	s_nop 0
	global_load_lds_dwordx4 v[224:225], off
	s_barrier
	s_waitcnt lgkmcnt(0)
	s_setprio 1
	s_waitcnt lgkmcnt(0)
	v_mfma_f32_16x16x32_bf16 v[118:121], v[208:211], v[176:179], v[118:121]
	v_mfma_f32_16x16x32_bf16 v[114:117], v[216:219], v[176:179], v[114:117]
	v_mfma_f32_16x16x32_bf16 v[102:105], v[208:211], v[184:187], v[102:105]
	v_mfma_f32_16x16x32_bf16 v[98:101], v[216:219], v[184:187], v[98:101]
	v_mfma_f32_16x16x32_bf16 v[86:89], v[208:211], v[192:195], v[86:89]
	v_mfma_f32_16x16x32_bf16 v[82:85], v[216:219], v[192:195], v[82:85]
	v_mfma_f32_16x16x32_bf16 v[70:73], v[208:211], v[200:203], v[70:73]
	v_mfma_f32_16x16x32_bf16 v[66:69], v[216:219], v[200:203], v[66:69]
	v_mfma_f32_16x16x32_bf16 v[118:121], v[212:215], v[180:183], v[118:121]
	v_mfma_f32_16x16x32_bf16 v[114:117], v[220:223], v[180:183], v[114:117]
	v_mfma_f32_16x16x32_bf16 v[102:105], v[212:215], v[188:191], v[102:105]
	v_mfma_f32_16x16x32_bf16 v[98:101], v[220:223], v[188:191], v[98:101]
	v_mfma_f32_16x16x32_bf16 v[86:89], v[212:215], v[196:199], v[86:89]
	v_mfma_f32_16x16x32_bf16 v[82:85], v[220:223], v[196:199], v[82:85]
	v_mfma_f32_16x16x32_bf16 v[70:73], v[212:215], v[204:207], v[70:73]
	v_mfma_f32_16x16x32_bf16 v[66:69], v[220:223], v[204:207], v[66:69]
	s_setprio 0
	s_mov_b32 m0, s40
	v_lshl_add_u64 v[226:227], s[34:35], 0, v[130:131]
	s_barrier
	ds_read_b128 v[176:179], v145 offset:16384
	ds_read_b128 v[180:183], v145 offset:17408
	ds_read_b128 v[184:187], v145 offset:18432
	ds_read_b128 v[188:191], v145 offset:19456
	ds_read_b128 v[192:195], v145 offset:20480
	ds_read_b128 v[196:199], v145 offset:21504
	ds_read_b128 v[200:203], v145 offset:22528
	ds_read_b128 v[204:207], v145 offset:23552
	global_load_lds_dwordx4 v[226:227], off
	v_lshl_add_u64 v[228:229], s[34:35], 0, v[132:133]
	s_mov_b32 m0, s42
	s_nop 0
	global_load_lds_dwordx4 v[228:229], off
	s_barrier
	s_waitcnt lgkmcnt(0)
	s_setprio 1
	s_waitcnt lgkmcnt(0)
	v_mfma_f32_16x16x32_bf16 v[62:65], v[138:141], v[176:179], v[62:65]
	v_mfma_f32_16x16x32_bf16 v[58:61], v[168:171], v[176:179], v[58:61]
	v_mfma_f32_16x16x32_bf16 v[46:49], v[138:141], v[184:187], v[46:49]
	v_mfma_f32_16x16x32_bf16 v[42:45], v[168:171], v[184:187], v[42:45]
	v_mfma_f32_16x16x32_bf16 v[30:33], v[138:141], v[192:195], v[30:33]
	v_mfma_f32_16x16x32_bf16 v[26:29], v[168:171], v[192:195], v[26:29]
	v_mfma_f32_16x16x32_bf16 v[14:17], v[138:141], v[200:203], v[14:17]
	v_mfma_f32_16x16x32_bf16 v[10:13], v[168:171], v[200:203], v[10:13]
	v_mfma_f32_16x16x32_bf16 v[62:65], v[164:167], v[180:183], v[62:65]
	v_mfma_f32_16x16x32_bf16 v[58:61], v[172:175], v[180:183], v[58:61]
	v_mfma_f32_16x16x32_bf16 v[46:49], v[164:167], v[188:191], v[46:49]
	v_mfma_f32_16x16x32_bf16 v[42:45], v[172:175], v[188:191], v[42:45]
	v_mfma_f32_16x16x32_bf16 v[30:33], v[164:167], v[196:199], v[30:33]
	v_mfma_f32_16x16x32_bf16 v[26:29], v[172:175], v[196:199], v[26:29]
	v_mfma_f32_16x16x32_bf16 v[14:17], v[164:167], v[204:207], v[14:17]
	v_mfma_f32_16x16x32_bf16 v[10:13], v[172:175], v[204:207], v[10:13]
	s_setprio 0
	s_barrier
; #define PG8_STAGE(bufoff, gbase, voff) do { _Pragma("unroll") for (int _i = 0; _i < 2; ++_i) \
;         __builtin_amdgcn_global_load_lds((const unsigned*)((const char*)(gbase) + (voff)[_i]), (PG8_LAS unsigned*)(lds + (bufoff) + ldsw + _i * 8192), 16, 0, 0); } while (0)
; #define PG8_LDA(dst, b, h) do { _Pragma("unroll") for (int m = 0; m < 4; ++m) _Pragma("unroll") for (int k = 0; k < 2; ++k) dst[m][k] = *(const PG8_LAS bf16x8*)(lds + PG8_SA(b, h) + aoff + m * 2048 + k * 1024); } while (0)
; #define PG8_LDB(dst, b, h) do { _Pragma("unroll") for (int n = 0; n < 2; ++n) _Pragma("unroll") for (int k = 0; k < 2; ++k) dst[n][k] = *(const PG8_LAS bf16x8*)(lds + PG8_SB(b, h) + boff + n * 2048 + k * 1024); } while (0)
; #define PG8_MMA(ai, bj, At, Bt) do { __builtin_amdgcn_s_setprio(1); _Pragma("unroll") for (int m = 0; m < 4; ++m) _Pragma("unroll") for (int n = 0; n < 2; ++n) _Pragma("unroll") for (int k = 0; k < 2; ++k) \
;         acc[ai][bj][m][n] = __builtin_amdgcn_mfma_f32_16x16x32_bf16(Bt[n][k], At[m][k], acc[ai][bj][m][n], 0, 0, 0); __builtin_amdgcn_s_setprio(0); } while (0)
; #define PG8_WAIT_V(n) asm volatile("s_waitcnt vmcnt(" #n ")" ::: "memory")
; #define PG8_WAIT_L(n) asm volatile("s_waitcnt lgkmcnt(" #n ")" ::: "memory")
; #define PG8_BAR __builtin_amdgcn_s_barrier()
; #define PG8_SCHED __builtin_amdgcn_sched_barrier(0)
; template <class Epi, class Sched>
; __device__ __forceinline__ void gemm_phase(PG8_LAS unsigned char* lds, const Gemm g, const Sched& S, const Epi& E) {
;     ...
;             PG8_STAGE(PG8_SB(0, 1), b2 + hstep, voffB);
;             PG8_WAIT_V(6); PG8_BAR; PG8_MMA(1, 1, At, B1); PG8_BAR;
;             PG8_LDB(B0, 1, 0); PG8_SCHED; PG8_LDA(At, 1, 0); PG8_STAGE(PG8_SA(0, 1), a2 + hstep, voffA);
;             PG8_WAIT_L(8); PG8_BAR; PG8_WAIT_L(0); PG8_MMA(0, 0, At, B0); PG8_BAR; PG8_SCHED;
;             PG8_LDB(B1, 1, 1); PG8_STAGE(PG8_SB(1, 0), b3, voffB);
;             PG8_BAR; PG8_WAIT_L(0); PG8_MMA(0, 1, At, B1); PG8_BAR;
;             PG8_LDA(At, 1, 1); PG8_STAGE(PG8_SA(1, 0), a3, voffA);
;             PG8_BAR; PG8_WAIT_L(0); PG8_MMA(1, 0, At, B0); PG8_BAR; PG8_SCHED;
	s_add_u32 s66, s30, 0x40000
	s_addc_u32 s67, s31, 0
	s_mov_b32 m0, s43
	v_lshl_add_u64 v[138:139], s[66:67], 0, v[130:131]
	global_load_lds_dwordx4 v[138:139], off
	v_lshl_add_u64 v[138:139], s[66:67], 0, v[132:133]
	s_mov_b32 m0, s44
	s_nop 0
	global_load_lds_dwordx4 v[138:139], off
	s_waitcnt vmcnt(6)
	s_barrier
	s_setprio 1
	v_mfma_f32_16x16x32_bf16 v[54:57], v[208:211], v[176:179], v[54:57]
	v_mfma_f32_16x16x32_bf16 v[50:53], v[216:219], v[176:179], v[50:53]
	v_mfma_f32_16x16x32_bf16 v[38:41], v[208:211], v[184:187], v[38:41]
	v_mfma_f32_16x16x32_bf16 v[34:37], v[216:219], v[184:187], v[34:37]
	v_mfma_f32_16x16x32_bf16 v[22:25], v[208:211], v[192:195], v[22:25]
	v_mfma_f32_16x16x32_bf16 v[18:21], v[216:219], v[192:195], v[18:21]
	v_mfma_f32_16x16x32_bf16 v[6:9], v[208:211], v[200:203], v[6:9]
	v_mfma_f32_16x16x32_bf16 v[2:5], v[216:219], v[200:203], v[2:5]
	v_mfma_f32_16x16x32_bf16 v[54:57], v[212:215], v[180:183], v[54:57]
	v_mfma_f32_16x16x32_bf16 v[50:53], v[220:223], v[180:183], v[50:53]
	v_mfma_f32_16x16x32_bf16 v[38:41], v[212:215], v[188:191], v[38:41]
	v_mfma_f32_16x16x32_bf16 v[34:37], v[220:223], v[188:191], v[34:37]
	v_mfma_f32_16x16x32_bf16 v[22:25], v[212:215], v[196:199], v[22:25]
	v_mfma_f32_16x16x32_bf16 v[18:21], v[220:223], v[196:199], v[18:21]
	v_mfma_f32_16x16x32_bf16 v[6:9], v[212:215], v[204:207], v[6:9]
	v_mfma_f32_16x16x32_bf16 v[2:5], v[220:223], v[204:207], v[2:5]
	s_setprio 0
	s_barrier
	ds_read_b128 v[138:141], v155
	ds_read_b128 v[164:167], v156
	ds_read_b128 v[168:171], v157
	ds_read_b128 v[172:175], v158
	s_add_u32 s34, s34, 0x40000
	s_addc_u32 s35, s35, 0
	s_mov_b32 m0, s45
	v_lshl_add_u64 v[208:209], s[34:35], 0, v[130:131]
	ds_read_b128 v[176:179], v145 offset:32768
	ds_read_b128 v[180:183], v145 offset:33792
	ds_read_b128 v[184:187], v145 offset:34816
	ds_read_b128 v[188:191], v145 offset:35840
	ds_read_b128 v[192:195], v145 offset:36864
	ds_read_b128 v[196:199], v145 offset:37888
	ds_read_b128 v[200:203], v145 offset:38912
	ds_read_b128 v[204:207], v145 offset:39936
	global_load_lds_dwordx4 v[208:209], off
	v_lshl_add_u64 v[208:209], s[34:35], 0, v[132:133]
	s_mov_b32 m0, s46
	s_nop 0
	global_load_lds_dwordx4 v[208:209], off
	s_waitcnt lgkmcnt(8)
	s_barrier
	s_waitcnt lgkmcnt(0)
	s_setprio 1
	s_waitcnt lgkmcnt(0)
	v_mfma_f32_16x16x32_bf16 v[126:129], v[138:141], v[176:179], v[126:129]
	v_mfma_f32_16x16x32_bf16 v[122:125], v[168:171], v[176:179], v[122:125]
	v_mfma_f32_16x16x32_bf16 v[110:113], v[138:141], v[184:187], v[110:113]
	v_mfma_f32_16x16x32_bf16 v[106:109], v[168:171], v[184:187], v[106:109]
	v_mfma_f32_16x16x32_bf16 v[94:97], v[138:141], v[192:195], v[94:97]
	v_mfma_f32_16x16x32_bf16 v[90:93], v[168:171], v[192:195], v[90:93]
	v_mfma_f32_16x16x32_bf16 v[78:81], v[138:141], v[200:203], v[78:81]
	v_mfma_f32_16x16x32_bf16 v[74:77], v[168:171], v[200:203], v[74:77]
	v_mfma_f32_16x16x32_bf16 v[126:129], v[164:167], v[180:183], v[126:129]
	v_mfma_f32_16x16x32_bf16 v[122:125], v[172:175], v[180:183], v[122:125]
	v_mfma_f32_16x16x32_bf16 v[110:113], v[164:167], v[188:191], v[110:113]
	v_mfma_f32_16x16x32_bf16 v[106:109], v[172:175], v[188:191], v[106:109]
	v_mfma_f32_16x16x32_bf16 v[94:97], v[164:167], v[196:199], v[94:97]
	v_mfma_f32_16x16x32_bf16 v[90:93], v[172:175], v[196:199], v[90:93]
	v_mfma_f32_16x16x32_bf16 v[78:81], v[164:167], v[204:207], v[78:81]
	v_mfma_f32_16x16x32_bf16 v[74:77], v[172:175], v[204:207], v[74:77]
	s_setprio 0
	s_barrier
	s_mov_b32 m0, s47
	v_lshl_add_u64 v[142:143], v[142:143], 0, s[8:9]
	ds_read_b128 v[208:211], v159
	ds_read_b128 v[212:215], v160
	ds_read_b128 v[216:219], v161
	ds_read_b128 v[220:223], v162
	global_load_lds_dwordx4 v[142:143], off
	v_lshl_add_u64 v[142:143], v[224:225], 0, s[8:9]
	s_mov_b32 m0, s48
	s_nop 0
	global_load_lds_dwordx4 v[142:143], off
	s_barrier
	s_waitcnt lgkmcnt(0)
	s_setprio 1
	s_waitcnt lgkmcnt(0)
	v_mfma_f32_16x16x32_bf16 v[118:121], v[208:211], v[176:179], v[118:121]
	v_mfma_f32_16x16x32_bf16 v[114:117], v[216:219], v[176:179], v[114:117]
	v_mfma_f32_16x16x32_bf16 v[102:105], v[208:211], v[184:187], v[102:105]
	v_mfma_f32_16x16x32_bf16 v[98:101], v[216:219], v[184:187], v[98:101]
	v_mfma_f32_16x16x32_bf16 v[86:89], v[208:211], v[192:195], v[86:89]
	v_mfma_f32_16x16x32_bf16 v[82:85], v[216:219], v[192:195], v[82:85]
	v_mfma_f32_16x16x32_bf16 v[70:73], v[208:211], v[200:203], v[70:73]
	v_mfma_f32_16x16x32_bf16 v[66:69], v[216:219], v[200:203], v[66:69]
	v_mfma_f32_16x16x32_bf16 v[118:121], v[212:215], v[180:183], v[118:121]
	v_mfma_f32_16x16x32_bf16 v[114:117], v[220:223], v[180:183], v[114:117]
	v_mfma_f32_16x16x32_bf16 v[102:105], v[212:215], v[188:191], v[102:105]
	v_mfma_f32_16x16x32_bf16 v[98:101], v[220:223], v[188:191], v[98:101]
	v_mfma_f32_16x16x32_bf16 v[86:89], v[212:215], v[196:199], v[86:89]
	v_mfma_f32_16x16x32_bf16 v[82:85], v[220:223], v[196:199], v[82:85]
	v_mfma_f32_16x16x32_bf16 v[70:73], v[212:215], v[204:207], v[70:73]
	v_mfma_f32_16x16x32_bf16 v[66:69], v[220:223], v[204:207], v[66:69]
	s_setprio 0
	s_mov_b32 m0, s49
	v_lshl_add_u64 v[142:143], v[226:227], 0, s[8:9]
	s_barrier
	ds_read_b128 v[176:179], v145 offset:49152
	ds_read_b128 v[180:183], v145 offset:50176
	ds_read_b128 v[184:187], v145 offset:51200
	ds_read_b128 v[188:191], v145 offset:52224
	ds_read_b128 v[192:195], v145 offset:53248
	ds_read_b128 v[196:199], v145 offset:54272
	ds_read_b128 v[200:203], v145 offset:55296
	ds_read_b128 v[204:207], v145 offset:56320
	global_load_lds_dwordx4 v[142:143], off
	v_lshl_add_u64 v[142:143], v[228:229], 0, s[8:9]
	s_mov_b32 m0, s50
	s_nop 0
	global_load_lds_dwordx4 v[142:143], off
	s_barrier
; #define PG8_STAGE(bufoff, gbase, voff) do { _Pragma("unroll") for (int _i = 0; _i < 2; ++_i) \
;         __builtin_amdgcn_global_load_lds((const unsigned*)((const char*)(gbase) + (voff)[_i]), (PG8_LAS unsigned*)(lds + (bufoff) + ldsw + _i * 8192), 16, 0, 0); } while (0)
; #define PG8_MMA(ai, bj, At, Bt) do { __builtin_amdgcn_s_setprio(1); _Pragma("unroll") for (int m = 0; m < 4; ++m) _Pragma("unroll") for (int n = 0; n < 2; ++n) _Pragma("unroll") for (int k = 0; k < 2; ++k) \
;         acc[ai][bj][m][n] = __builtin_amdgcn_mfma_f32_16x16x32_bf16(Bt[n][k], At[m][k], acc[ai][bj][m][n], 0, 0, 0); __builtin_amdgcn_s_setprio(0); } while (0)
; #define PG8_WAIT_V(n) asm volatile("s_waitcnt vmcnt(" #n ")" ::: "memory")
; #define PG8_WAIT_L(n) asm volatile("s_waitcnt lgkmcnt(" #n ")" ::: "memory")
; #define PG8_BAR __builtin_amdgcn_s_barrier()
; #define PG8_SCHED __builtin_amdgcn_sched_barrier(0)
; template <class Epi, class Sched>
; __device__ __forceinline__ void gemm_phase(PG8_LAS unsigned char* lds, const Gemm g, const Sched& S, const Epi& E) {
;     ...
;             PG8_BAR; PG8_WAIT_L(0); PG8_MMA(1, 0, At, B0); PG8_BAR; PG8_SCHED;
;             PG8_STAGE(PG8_SB(1, 1), b3 + hstep, voffB);
;             PG8_WAIT_V(6); PG8_BAR; PG8_MMA(1, 1, At, B1); PG8_BAR;
;   __device__ __forceinline__ void operator()(const acc8_t& acc, const pg8::Unit& u, int wr, int wc, int fr, int fq) const {
;     u16* X1B = (u16*)(p.ws + OFF_X1B);
;     float* rss = (float*)(p.ws + OFF_ROWSS);
; #pragma unroll
;     for (int ai = 0; ai < 2; ai++)
; #pragma unroll
;       for (int m = 0; m < 4; m++) {
;         const int token = (int)EPI_TOKEN(u, ai, m);
;         const float* xr = xrow(p, token);
;         float ss = 0.f;
; #pragma unroll
;         for (int bj = 0; bj < 2; bj++)
; #pragma unroll
;           for (int n = 0; n < 2; n++) {
;             const int f = EPI_COL(u, bj, n);
;             const float4 xv = *(const float4*)(xr + f);
;             const float4 o = make_float4(xv.x + acc[ai][bj][m][n][0], xv.y + acc[ai][bj][m][n][1], xv.z + acc[ai][bj][m][n][2], xv.w + acc[ai][bj][m][n][3]);
	s_waitcnt lgkmcnt(0)
	s_setprio 1
	s_waitcnt lgkmcnt(0)
	v_mfma_f32_16x16x32_bf16 v[62:65], v[138:141], v[176:179], v[62:65]
	v_mfma_f32_16x16x32_bf16 v[58:61], v[168:171], v[176:179], v[58:61]
	v_mfma_f32_16x16x32_bf16 v[46:49], v[138:141], v[184:187], v[46:49]
	v_mfma_f32_16x16x32_bf16 v[42:45], v[168:171], v[184:187], v[42:45]
	v_mfma_f32_16x16x32_bf16 v[30:33], v[138:141], v[192:195], v[30:33]
	v_mfma_f32_16x16x32_bf16 v[26:29], v[168:171], v[192:195], v[26:29]
	v_mfma_f32_16x16x32_bf16 v[14:17], v[138:141], v[200:203], v[14:17]
	v_mfma_f32_16x16x32_bf16 v[10:13], v[168:171], v[200:203], v[10:13]
	v_mfma_f32_16x16x32_bf16 v[62:65], v[164:167], v[180:183], v[62:65]
	v_mfma_f32_16x16x32_bf16 v[58:61], v[172:175], v[180:183], v[58:61]
	v_mfma_f32_16x16x32_bf16 v[46:49], v[164:167], v[188:191], v[46:49]
	v_mfma_f32_16x16x32_bf16 v[42:45], v[172:175], v[188:191], v[42:45]
	v_mfma_f32_16x16x32_bf16 v[30:33], v[164:167], v[196:199], v[30:33]
	v_mfma_f32_16x16x32_bf16 v[26:29], v[172:175], v[196:199], v[26:29]
	v_mfma_f32_16x16x32_bf16 v[14:17], v[164:167], v[204:207], v[14:17]
	v_mfma_f32_16x16x32_bf16 v[10:13], v[172:175], v[204:207], v[10:13]
	s_setprio 0
	s_barrier
	s_add_u32 s30, s30, 0x40080
	s_addc_u32 s31, s31, 0
	s_mov_b32 m0, s51
	v_lshl_add_u64 v[138:139], s[30:31], 0, v[130:131]
	global_load_lds_dwordx4 v[138:139], off
	v_lshl_add_u64 v[138:139], s[30:31], 0, v[132:133]
	s_mov_b32 m0, s56
	s_nop 0
	global_load_lds_dwordx4 v[138:139], off
	s_waitcnt vmcnt(6)
	s_barrier
	s_setprio 1
	v_mfma_f32_16x16x32_bf16 v[54:57], v[208:211], v[176:179], v[54:57]
	v_mfma_f32_16x16x32_bf16 v[50:53], v[216:219], v[176:179], v[50:53]
	v_mfma_f32_16x16x32_bf16 v[38:41], v[208:211], v[184:187], v[38:41]
	v_mfma_f32_16x16x32_bf16 v[34:37], v[216:219], v[184:187], v[34:37]
	v_mfma_f32_16x16x32_bf16 v[22:25], v[208:211], v[192:195], v[22:25]
	v_mfma_f32_16x16x32_bf16 v[18:21], v[216:219], v[192:195], v[18:21]
	v_mfma_f32_16x16x32_bf16 v[6:9], v[208:211], v[200:203], v[6:9]
	v_mfma_f32_16x16x32_bf16 v[2:5], v[216:219], v[200:203], v[2:5]
	v_mfma_f32_16x16x32_bf16 v[54:57], v[212:215], v[180:183], v[54:57]
	v_mfma_f32_16x16x32_bf16 v[50:53], v[220:223], v[180:183], v[50:53]
	v_mfma_f32_16x16x32_bf16 v[38:41], v[212:215], v[188:191], v[38:41]
	v_mfma_f32_16x16x32_bf16 v[34:37], v[220:223], v[188:191], v[34:37]
	v_mfma_f32_16x16x32_bf16 v[22:25], v[212:215], v[196:199], v[22:25]
	v_mfma_f32_16x16x32_bf16 v[18:21], v[220:223], v[196:199], v[18:21]
	v_mfma_f32_16x16x32_bf16 v[6:9], v[212:215], v[204:207], v[6:9]
	v_mfma_f32_16x16x32_bf16 v[2:5], v[220:223], v[204:207], v[2:5]
	s_setprio 0
	s_add_i32 s64, s64, 2
	s_add_u32 s28, s28, 0x100
	s_addc_u32 s29, s29, 0
	s_add_u32 s62, s62, 0x100
	s_addc_u32 s63, s63, 0
	s_cmp_gt_u32 s64, 13
	s_barrier
	s_cbranch_scc0 .LBB0_750
	v_readlane_b32 s64, v239, 0
	v_readlane_b32 s65, v239, 1
	v_lshl_add_u32 v140, s26, 8, v144
	v_readlane_b32 s66, v239, 2
	v_readlane_b32 s67, v239, 3
	s_mov_b64 s[52:53], s[64:65]
	v_add_u32_e32 v139, 0xffff8000, v140
	v_cmp_gt_i32_e32 vcc, s57, v140
	s_mov_b64 s[54:55], s[66:67]
	v_ashrrev_i32_e32 v141, 31, v140
	v_cndmask_b32_e32 v142, v139, v140, vcc
	v_mov_b32_e32 v139, s55
	v_mov_b32_e32 v163, s53
	v_lshl_or_b32 v138, s24, 8, v146
	v_cndmask_b32_e32 v143, 0, v141, vcc
	v_cndmask_b32_e32 v165, v139, v163, vcc
	v_mov_b32_e32 v139, s54
	v_mov_b32_e32 v163, s52
	v_cndmask_b32_e32 v164, v139, v163, vcc
	v_lshlrev_b64 v[142:143], 12, v[142:143]
	v_ashrrev_i32_e32 v139, 31, v138
	v_lshl_add_u64 v[164:165], v[164:165], 0, v[142:143]
	v_lshlrev_b64 v[142:143], 2, v[138:139]
	v_bfe_u32 v237, v0, 4, 1
	v_mul_u32_u24_e32 v237, 12, v237
	v_add_u32_e32 v138, v138, v237
	v_lshl_add_u64 v[168:169], v[164:165], 0, v[142:143]
	global_load_dwordx4 v[164:167], v[168:169], off nt
	global_load_dwordx4 v[176:179], v[168:169], off offset:64 nt
	global_load_dwordx4 v[180:183], v[168:169], off offset:512 nt
	global_load_dwordx4 v[184:187], v[168:169], off offset:576 nt
	v_lshlrev_b64 v[170:171], 11, v[140:141]
	v_lshlrev_b64 v[172:173], 12, v[140:141]
	v_lshl_add_u64 v[170:171], s[10:11], 0, v[170:171]
	v_lshl_add_u64 v[172:173], s[86:87], 0, v[172:173]
	v_lshl_add_u64 v[172:173], v[172:173], 0, v[142:143]
	v_lshl_add_u64 v[170:171], v[138:139], 1, v[170:171]
	v_readlane_b32 s68, v239, 4
	v_readlane_b32 s69, v239, 5
	v_readlane_b32 s70, v239, 6
	v_readlane_b32 s71, v239, 7
	v_readlane_b32 s72, v239, 8
	v_readlane_b32 s73, v239, 9
	v_readlane_b32 s74, v239, 10
	v_readlane_b32 s75, v239, 11
	v_readlane_b32 s76, v239, 12
	v_readlane_b32 s77, v239, 13
	v_readlane_b32 s78, v239, 14
	v_readlane_b32 s79, v239, 15
	s_waitcnt vmcnt(0)
;   __device__ __forceinline__ void operator()(const acc8_t& acc, const pg8::Unit& u, int wr, int wc, int fr, int fq) const {
;     ...
;       for (int m = 0; m < 4; m++) {
;         const int token = (int)EPI_TOKEN(u, ai, m);
;         const float* xr = xrow(p, token);
;         float ss = 0.f;
; #pragma unroll
;         for (int bj = 0; bj < 2; bj++)
; #pragma unroll
;           for (int n = 0; n < 2; n++) {
;             const int f = EPI_COL(u, bj, n);
;             const float4 xv = *(const float4*)(xr + f);
;             const float4 o = make_float4(xv.x + acc[ai][bj][m][n][0], xv.y + acc[ai][bj][m][n][1], xv.z + acc[ai][bj][m][n][2], xv.w + acc[ai][bj][m][n][3]);
;             ss += o.x * o.x + o.y * o.y + o.z * o.z + o.w * o.w;
;             *(float4*)(p.out + O_Y + (size_t)token * 1024 + f) = o;
;             uint2 ob; ob.x = pack2(o.x, o.y); ob.y = pack2(o.z, o.w);
;             *(uint2*)(X1B + (size_t)token * 1024 + f) = ob;
;           }
;         ss = xsum16(ss);
;         ss = xsum32(ss);
;         if (fq == 0) atomicAdd(rss + token, ss);
	v_pk_add_f32 v[126:127], v[126:127], v[164:165]
	v_pk_add_f32 v[128:129], v[128:129], v[166:167]
	v_cvt_pk_bf16_f32 v230, v126, v127
	v_cvt_pk_bf16_f32 v231, v128, v129
	global_store_dwordx4 v[172:173], v[126:129], off
	v_mul_f32_e32 v174, v129, v129
	v_pk_add_f32 v[122:123], v[122:123], v[176:177]
	v_pk_add_f32 v[124:125], v[124:125], v[178:179]
	v_cvt_pk_bf16_f32 v232, v122, v123
	v_cvt_pk_bf16_f32 v233, v124, v125
	global_store_dwordx4 v[172:173], v[122:125], off offset:64
	v_permlane16_swap_b32_e32 v230, v232
	v_permlane16_swap_b32_e32 v231, v233
	global_store_dwordx4 v[170:171], v[230:233], off
	v_pk_add_f32 v[118:119], v[118:119], v[180:181]
	v_pk_add_f32 v[120:121], v[120:121], v[182:183]
	v_cvt_pk_bf16_f32 v234, v118, v119
	v_cvt_pk_bf16_f32 v235, v120, v121
	global_store_dwordx4 v[172:173], v[118:121], off offset:512
	v_mul_f32_e32 v168, v127, v127
	v_pk_fma_f32 v[126:127], v[126:127], v[126:127], v[168:169] op_sel_hi:[1,1,0]
	v_mul_f32_e32 v168, v125, v125
	v_pk_fma_f32 v[126:127], v[128:129], v[128:129], v[126:127]
	v_mul_f32_e32 v128, v123, v123
	v_pk_fma_f32 v[122:123], v[122:123], v[122:123], v[128:129] op_sel_hi:[1,1,0]
	v_pk_add_f32 v[126:127], v[174:175], v[126:127] op_sel_hi:[0,1]
	v_pk_fma_f32 v[122:123], v[124:125], v[124:125], v[122:123]
	v_mul_f32_e32 v124, v119, v119
	v_pk_add_f32 v[122:123], v[168:169], v[122:123] op_sel_hi:[0,1]
	v_pk_fma_f32 v[118:119], v[118:119], v[118:119], v[124:125] op_sel_hi:[1,1,0]
	v_pk_add_f32 v[122:123], v[126:127], v[122:123]
	v_mul_f32_e32 v126, v121, v121
	v_pk_fma_f32 v[118:119], v[120:121], v[120:121], v[118:119]
	v_pk_add_f32 v[114:115], v[114:115], v[184:185]
	v_pk_add_f32 v[116:117], v[116:117], v[186:187]
	v_mul_f32_e32 v120, v115, v115
	v_pk_add_f32 v[118:119], v[126:127], v[118:119] op_sel_hi:[0,1]
	global_store_dwordx4 v[172:173], v[114:117], off offset:576
	v_cvt_pk_bf16_f32 v236, v114, v115
	v_pk_add_f32 v[118:119], v[122:123], v[118:119]
	v_pk_fma_f32 v[114:115], v[114:115], v[114:115], v[120:121] op_sel_hi:[1,1,0]
	v_mul_f32_e32 v122, v117, v117
	v_pk_fma_f32 v[114:115], v[116:117], v[116:117], v[114:115]
	v_cvt_pk_bf16_f32 v237, v116, v117
	v_pk_add_f32 v[114:115], v[122:123], v[114:115] op_sel_hi:[0,1]
	v_pk_add_f32 v[114:115], v[118:119], v[114:115]
	v_permlane16_swap_b32_e32 v234, v236
	v_permlane16_swap_b32_e32 v235, v237
	global_store_dwordx4 v[170:171], v[234:237], off offset:256
	v_mov_b32_e32 v115, v114
	s_nop 1
	v_permlane16_swap_b32_e32 v114, v115
	v_add_f32_e32 v114, v114, v115
	v_mov_b32_e32 v115, v114
	s_nop 1
	v_permlane32_swap_b32_e32 v114, v115
	s_and_saveexec_b64 s[24:25], s[4:5]
	s_cbranch_execz .LBB0_753
	v_add_f32_e32 v116, v114, v115
	v_lshl_add_u64 v[114:115], v[140:141], 2, s[12:13]
	global_atomic_add_f32 v[114:115], v116, off
.LBB0_753:
	s_or_b64 exec, exec, s[24:25]
	v_readlane_b32 s64, v239, 0
	v_readlane_b32 s65, v239, 1
	v_readlane_b32 s66, v239, 2
	v_readlane_b32 s67, v239, 3
	s_mov_b64 s[52:53], s[64:65]
	v_or_b32_e32 v114, 16, v140
	s_mov_b64 s[54:55], s[66:67]
	v_ashrrev_i32_e32 v115, 31, v114
	v_add_u32_e32 v116, 0xffff8010, v140
	v_cmp_gt_i32_e32 vcc, s57, v114
	v_mov_b32_e32 v118, s55
	v_mov_b32_e32 v119, s53
	v_cndmask_b32_e32 v117, 0, v115, vcc
	v_cndmask_b32_e32 v116, v116, v114, vcc
	v_cndmask_b32_e32 v119, v118, v119, vcc
	v_mov_b32_e32 v118, s54
	v_mov_b32_e32 v120, s52
	v_cndmask_b32_e32 v118, v118, v120, vcc
	v_lshlrev_b64 v[116:117], 12, v[116:117]
	v_lshl_add_u64 v[116:117], v[118:119], 0, v[116:117]
	v_lshl_add_u64 v[120:121], v[116:117], 0, v[142:143]
	global_load_dwordx4 v[116:119], v[120:121], off nt
	global_load_dwordx4 v[176:179], v[120:121], off offset:64 nt
	global_load_dwordx4 v[180:183], v[120:121], off offset:512 nt
	global_load_dwordx4 v[184:187], v[120:121], off offset:576 nt
	v_lshlrev_b64 v[122:123], 11, v[114:115]
	v_lshlrev_b64 v[124:125], 12, v[114:115]
	v_lshl_add_u64 v[122:123], s[10:11], 0, v[122:123]
	v_lshl_add_u64 v[124:125], s[86:87], 0, v[124:125]
	v_lshl_add_u64 v[124:125], v[124:125], 0, v[142:143]
	v_lshl_add_u64 v[122:123], v[138:139], 1, v[122:123]
	v_readlane_b32 s68, v239, 4
	v_readlane_b32 s69, v239, 5
	v_readlane_b32 s70, v239, 6
	v_readlane_b32 s71, v239, 7
	v_readlane_b32 s72, v239, 8
	v_readlane_b32 s73, v239, 9
	v_readlane_b32 s74, v239, 10
	v_readlane_b32 s75, v239, 11
	v_readlane_b32 s76, v239, 12
	v_readlane_b32 s77, v239, 13
	v_readlane_b32 s78, v239, 14
	v_readlane_b32 s79, v239, 15
	s_waitcnt vmcnt(0)
	v_pk_add_f32 v[110:111], v[110:111], v[116:117]
	v_pk_add_f32 v[112:113], v[112:113], v[118:119]
	v_cvt_pk_bf16_f32 v230, v110, v111
	v_cvt_pk_bf16_f32 v231, v112, v113
	global_store_dwordx4 v[124:125], v[110:113], off
	v_mul_f32_e32 v126, v113, v113
	v_pk_add_f32 v[106:107], v[106:107], v[176:177]
	v_pk_add_f32 v[108:109], v[108:109], v[178:179]
	v_cvt_pk_bf16_f32 v232, v106, v107
	v_cvt_pk_bf16_f32 v233, v108, v109
	global_store_dwordx4 v[124:125], v[106:109], off offset:64
	v_permlane16_swap_b32_e32 v230, v232
	v_permlane16_swap_b32_e32 v231, v233
	global_store_dwordx4 v[122:123], v[230:233], off
	v_pk_add_f32 v[102:103], v[102:103], v[180:181]
	v_pk_add_f32 v[104:105], v[104:105], v[182:183]
	v_cvt_pk_bf16_f32 v234, v102, v103
	v_cvt_pk_bf16_f32 v235, v104, v105
	global_store_dwordx4 v[124:125], v[102:105], off offset:512
	v_mul_f32_e32 v120, v111, v111
	v_pk_fma_f32 v[110:111], v[110:111], v[110:111], v[120:121] op_sel_hi:[1,1,0]
	v_mul_f32_e32 v120, v109, v109
	v_pk_fma_f32 v[110:111], v[112:113], v[112:113], v[110:111]
	v_mul_f32_e32 v112, v107, v107
	v_pk_fma_f32 v[106:107], v[106:107], v[106:107], v[112:113] op_sel_hi:[1,1,0]
	v_pk_add_f32 v[110:111], v[126:127], v[110:111] op_sel_hi:[0,1]
	v_pk_fma_f32 v[106:107], v[108:109], v[108:109], v[106:107]
	v_mul_f32_e32 v108, v103, v103
	v_pk_add_f32 v[106:107], v[120:121], v[106:107] op_sel_hi:[0,1]
	v_pk_fma_f32 v[102:103], v[102:103], v[102:103], v[108:109] op_sel_hi:[1,1,0]
	v_pk_add_f32 v[106:107], v[110:111], v[106:107]
	v_mul_f32_e32 v110, v105, v105
	v_pk_fma_f32 v[102:103], v[104:105], v[104:105], v[102:103]
	v_pk_add_f32 v[98:99], v[98:99], v[184:185]
	v_pk_add_f32 v[100:101], v[100:101], v[186:187]
	v_mul_f32_e32 v104, v99, v99
	v_pk_add_f32 v[102:103], v[110:111], v[102:103] op_sel_hi:[0,1]
	global_store_dwordx4 v[124:125], v[98:101], off offset:576
	v_cvt_pk_bf16_f32 v236, v98, v99
	v_pk_add_f32 v[102:103], v[106:107], v[102:103]
	v_pk_fma_f32 v[98:99], v[98:99], v[98:99], v[104:105] op_sel_hi:[1,1,0]
	v_mul_f32_e32 v106, v101, v101
	v_pk_fma_f32 v[98:99], v[100:101], v[100:101], v[98:99]
	v_cvt_pk_bf16_f32 v237, v100, v101
	v_pk_add_f32 v[98:99], v[106:107], v[98:99] op_sel_hi:[0,1]
	v_pk_add_f32 v[98:99], v[102:103], v[98:99]
	v_permlane16_swap_b32_e32 v234, v236
	v_permlane16_swap_b32_e32 v235, v237
	global_store_dwordx4 v[122:123], v[234:237], off offset:256
	v_mov_b32_e32 v99, v98
	s_nop 1
	v_permlane16_swap_b32_e32 v98, v99
	v_add_f32_e32 v98, v98, v99
	v_mov_b32_e32 v99, v98
	s_nop 1
	v_permlane32_swap_b32_e32 v98, v99
	s_and_saveexec_b64 s[24:25], s[4:5]
	s_cbranch_execz .LBB0_755
;   __device__ __forceinline__ void operator()(const acc8_t& acc, const pg8::Unit& u, int wr, int wc, int fr, int fq) const {
;     ...
;       for (int m = 0; m < 4; m++) {
;         const int token = (int)EPI_TOKEN(u, ai, m);
;         const float* xr = xrow(p, token);
;         float ss = 0.f;
; #pragma unroll
;         for (int bj = 0; bj < 2; bj++)
; #pragma unroll
;           for (int n = 0; n < 2; n++) {
;             const int f = EPI_COL(u, bj, n);
;             const float4 xv = *(const float4*)(xr + f);
;             const float4 o = make_float4(xv.x + acc[ai][bj][m][n][0], xv.y + acc[ai][bj][m][n][1], xv.z + acc[ai][bj][m][n][2], xv.w + acc[ai][bj][m][n][3]);
;             ss += o.x * o.x + o.y * o.y + o.z * o.z + o.w * o.w;
;             *(float4*)(p.out + O_Y + (size_t)token * 1024 + f) = o;
;             uint2 ob; ob.x = pack2(o.x, o.y); ob.y = pack2(o.z, o.w);
;             *(uint2*)(X1B + (size_t)token * 1024 + f) = ob;
;           }
;         ss = xsum16(ss);
;         ss = xsum32(ss);
;         if (fq == 0) atomicAdd(rss + token, ss);
	v_add_f32_e32 v100, v98, v99
	v_lshl_add_u64 v[98:99], v[114:115], 2, s[12:13]
	global_atomic_add_f32 v[98:99], v100, off
.LBB0_755:
	s_or_b64 exec, exec, s[24:25]
	v_readlane_b32 s64, v239, 0
	v_readlane_b32 s65, v239, 1
	v_readlane_b32 s66, v239, 2
	v_readlane_b32 s67, v239, 3
	s_mov_b64 s[52:53], s[64:65]
	v_or_b32_e32 v98, 32, v140
	s_mov_b64 s[54:55], s[66:67]
	v_ashrrev_i32_e32 v99, 31, v98
	v_add_u32_e32 v100, 0xffff8020, v140
	v_cmp_gt_i32_e32 vcc, s57, v98
	v_mov_b32_e32 v102, s55
	v_mov_b32_e32 v103, s53
	v_cndmask_b32_e32 v101, 0, v99, vcc
	v_cndmask_b32_e32 v100, v100, v98, vcc
	v_cndmask_b32_e32 v103, v102, v103, vcc
	v_mov_b32_e32 v102, s54
	v_mov_b32_e32 v104, s52
	v_cndmask_b32_e32 v102, v102, v104, vcc
	v_lshlrev_b64 v[100:101], 12, v[100:101]
	v_lshl_add_u64 v[100:101], v[102:103], 0, v[100:101]
	v_lshl_add_u64 v[104:105], v[100:101], 0, v[142:143]
	global_load_dwordx4 v[100:103], v[104:105], off nt
	global_load_dwordx4 v[176:179], v[104:105], off offset:64 nt
	global_load_dwordx4 v[180:183], v[104:105], off offset:512 nt
	global_load_dwordx4 v[184:187], v[104:105], off offset:576 nt
	v_lshlrev_b64 v[106:107], 11, v[98:99]
	v_lshlrev_b64 v[108:109], 12, v[98:99]
	v_lshl_add_u64 v[106:107], s[10:11], 0, v[106:107]
	v_lshl_add_u64 v[108:109], s[86:87], 0, v[108:109]
	v_lshl_add_u64 v[108:109], v[108:109], 0, v[142:143]
	v_lshl_add_u64 v[106:107], v[138:139], 1, v[106:107]
	v_readlane_b32 s68, v239, 4
	v_readlane_b32 s69, v239, 5
	v_readlane_b32 s70, v239, 6
	v_readlane_b32 s71, v239, 7
	v_readlane_b32 s72, v239, 8
	v_readlane_b32 s73, v239, 9
	v_readlane_b32 s74, v239, 10
	v_readlane_b32 s75, v239, 11
	v_readlane_b32 s76, v239, 12
	v_readlane_b32 s77, v239, 13
	v_readlane_b32 s78, v239, 14
	v_readlane_b32 s79, v239, 15
	s_waitcnt vmcnt(0)
	v_pk_add_f32 v[94:95], v[94:95], v[100:101]
	v_pk_add_f32 v[96:97], v[96:97], v[102:103]
	v_cvt_pk_bf16_f32 v230, v94, v95
	v_cvt_pk_bf16_f32 v231, v96, v97
	global_store_dwordx4 v[108:109], v[94:97], off
	v_mul_f32_e32 v110, v97, v97
	v_pk_add_f32 v[90:91], v[90:91], v[176:177]
	v_pk_add_f32 v[92:93], v[92:93], v[178:179]
	v_cvt_pk_bf16_f32 v232, v90, v91
	v_cvt_pk_bf16_f32 v233, v92, v93
	global_store_dwordx4 v[108:109], v[90:93], off offset:64
	v_permlane16_swap_b32_e32 v230, v232
	v_permlane16_swap_b32_e32 v231, v233
	global_store_dwordx4 v[106:107], v[230:233], off
	v_pk_add_f32 v[86:87], v[86:87], v[180:181]
	v_pk_add_f32 v[88:89], v[88:89], v[182:183]
	v_cvt_pk_bf16_f32 v234, v86, v87
	v_cvt_pk_bf16_f32 v235, v88, v89
	global_store_dwordx4 v[108:109], v[86:89], off offset:512
	v_mul_f32_e32 v104, v95, v95
	v_pk_fma_f32 v[94:95], v[94:95], v[94:95], v[104:105] op_sel_hi:[1,1,0]
	v_mul_f32_e32 v104, v93, v93
	v_pk_fma_f32 v[94:95], v[96:97], v[96:97], v[94:95]
	v_mul_f32_e32 v96, v91, v91
	v_pk_fma_f32 v[90:91], v[90:91], v[90:91], v[96:97] op_sel_hi:[1,1,0]
	v_pk_add_f32 v[94:95], v[110:111], v[94:95] op_sel_hi:[0,1]
	v_pk_fma_f32 v[90:91], v[92:93], v[92:93], v[90:91]
	v_mul_f32_e32 v92, v87, v87
	v_pk_add_f32 v[90:91], v[104:105], v[90:91] op_sel_hi:[0,1]
	v_pk_fma_f32 v[86:87], v[86:87], v[86:87], v[92:93] op_sel_hi:[1,1,0]
	v_pk_add_f32 v[90:91], v[94:95], v[90:91]
	v_mul_f32_e32 v94, v89, v89
	v_pk_fma_f32 v[86:87], v[88:89], v[88:89], v[86:87]
	v_pk_add_f32 v[82:83], v[82:83], v[184:185]
	v_pk_add_f32 v[84:85], v[84:85], v[186:187]
	v_mul_f32_e32 v88, v83, v83
	v_pk_add_f32 v[86:87], v[94:95], v[86:87] op_sel_hi:[0,1]
	global_store_dwordx4 v[108:109], v[82:85], off offset:576
	v_cvt_pk_bf16_f32 v236, v82, v83
	v_pk_add_f32 v[86:87], v[90:91], v[86:87]
	v_pk_fma_f32 v[82:83], v[82:83], v[82:83], v[88:89] op_sel_hi:[1,1,0]
	v_mul_f32_e32 v90, v85, v85
	v_pk_fma_f32 v[82:83], v[84:85], v[84:85], v[82:83]
	v_cvt_pk_bf16_f32 v237, v84, v85
	v_pk_add_f32 v[82:83], v[90:91], v[82:83] op_sel_hi:[0,1]
	v_pk_add_f32 v[82:83], v[86:87], v[82:83]
	v_permlane16_swap_b32_e32 v234, v236
	v_permlane16_swap_b32_e32 v235, v237
	global_store_dwordx4 v[106:107], v[234:237], off offset:256
	v_mov_b32_e32 v83, v82
	s_nop 1
	v_permlane16_swap_b32_e32 v82, v83
	v_add_f32_e32 v82, v82, v83
	v_mov_b32_e32 v83, v82
	s_nop 1
	v_permlane32_swap_b32_e32 v82, v83
	s_and_saveexec_b64 s[24:25], s[4:5]
	s_cbranch_execz .LBB0_757
	v_add_f32_e32 v84, v82, v83
	v_lshl_add_u64 v[82:83], v[98:99], 2, s[12:13]
	global_atomic_add_f32 v[82:83], v84, off
;   __device__ __forceinline__ void operator()(const acc8_t& acc, const pg8::Unit& u, int wr, int wc, int fr, int fq) const {
;     ...
;       for (int m = 0; m < 4; m++) {
;         const int token = (int)EPI_TOKEN(u, ai, m);
;         const float* xr = xrow(p, token);
;         float ss = 0.f;
; #pragma unroll
;         for (int bj = 0; bj < 2; bj++)
; #pragma unroll
;           for (int n = 0; n < 2; n++) {
;             const int f = EPI_COL(u, bj, n);
;             const float4 xv = *(const float4*)(xr + f);
;             const float4 o = make_float4(xv.x + acc[ai][bj][m][n][0], xv.y + acc[ai][bj][m][n][1], xv.z + acc[ai][bj][m][n][2], xv.w + acc[ai][bj][m][n][3]);
;             ss += o.x * o.x + o.y * o.y + o.z * o.z + o.w * o.w;
;             *(float4*)(p.out + O_Y + (size_t)token * 1024 + f) = o;
;             uint2 ob; ob.x = pack2(o.x, o.y); ob.y = pack2(o.z, o.w);
;             *(uint2*)(X1B + (size_t)token * 1024 + f) = ob;
;           }
;         ss = xsum16(ss);
;         ss = xsum32(ss);
;         if (fq == 0) atomicAdd(rss + token, ss);
.LBB0_757:
	s_or_b64 exec, exec, s[24:25]
	v_readlane_b32 s64, v239, 0
	v_readlane_b32 s65, v239, 1
	v_readlane_b32 s66, v239, 2
	v_readlane_b32 s67, v239, 3
	s_mov_b64 s[52:53], s[64:65]
	v_or_b32_e32 v82, 48, v140
	s_mov_b64 s[54:55], s[66:67]
	v_ashrrev_i32_e32 v83, 31, v82
	v_add_u32_e32 v84, 0xffff8030, v140
	v_cmp_gt_i32_e32 vcc, s57, v82
	v_mov_b32_e32 v86, s55
	v_mov_b32_e32 v87, s53
	v_cndmask_b32_e32 v85, 0, v83, vcc
	v_cndmask_b32_e32 v84, v84, v82, vcc
	v_cndmask_b32_e32 v87, v86, v87, vcc
	v_mov_b32_e32 v86, s54
	v_mov_b32_e32 v88, s52
	v_cndmask_b32_e32 v86, v86, v88, vcc
	v_lshlrev_b64 v[84:85], 12, v[84:85]
	v_lshl_add_u64 v[84:85], v[86:87], 0, v[84:85]
	v_lshl_add_u64 v[88:89], v[84:85], 0, v[142:143]
	global_load_dwordx4 v[84:87], v[88:89], off nt
	global_load_dwordx4 v[176:179], v[88:89], off offset:64 nt
	global_load_dwordx4 v[180:183], v[88:89], off offset:512 nt
	global_load_dwordx4 v[184:187], v[88:89], off offset:576 nt
	v_lshlrev_b64 v[90:91], 11, v[82:83]
	v_lshlrev_b64 v[92:93], 12, v[82:83]
	v_lshl_add_u64 v[90:91], s[10:11], 0, v[90:91]
	v_lshl_add_u64 v[92:93], s[86:87], 0, v[92:93]
	v_lshl_add_u64 v[92:93], v[92:93], 0, v[142:143]
	v_lshl_add_u64 v[90:91], v[138:139], 1, v[90:91]
	v_readlane_b32 s68, v239, 4
	v_readlane_b32 s69, v239, 5
	v_readlane_b32 s70, v239, 6
	v_readlane_b32 s71, v239, 7
	v_readlane_b32 s72, v239, 8
	v_readlane_b32 s73, v239, 9
	v_readlane_b32 s74, v239, 10
	v_readlane_b32 s75, v239, 11
	v_readlane_b32 s76, v239, 12
	v_readlane_b32 s77, v239, 13
	v_readlane_b32 s78, v239, 14
	v_readlane_b32 s79, v239, 15
	s_waitcnt vmcnt(0)
	v_pk_add_f32 v[78:79], v[78:79], v[84:85]
	v_pk_add_f32 v[80:81], v[80:81], v[86:87]
	v_cvt_pk_bf16_f32 v230, v78, v79
	v_cvt_pk_bf16_f32 v231, v80, v81
	global_store_dwordx4 v[92:93], v[78:81], off
	v_mul_f32_e32 v94, v81, v81
	v_pk_add_f32 v[74:75], v[74:75], v[176:177]
	v_pk_add_f32 v[76:77], v[76:77], v[178:179]
	v_cvt_pk_bf16_f32 v232, v74, v75
	v_cvt_pk_bf16_f32 v233, v76, v77
	global_store_dwordx4 v[92:93], v[74:77], off offset:64
	v_permlane16_swap_b32_e32 v230, v232
	v_permlane16_swap_b32_e32 v231, v233
	global_store_dwordx4 v[90:91], v[230:233], off
	v_pk_add_f32 v[70:71], v[70:71], v[180:181]
	v_pk_add_f32 v[72:73], v[72:73], v[182:183]
	v_cvt_pk_bf16_f32 v234, v70, v71
	v_cvt_pk_bf16_f32 v235, v72, v73
	global_store_dwordx4 v[92:93], v[70:73], off offset:512
	v_mul_f32_e32 v88, v79, v79
	v_pk_fma_f32 v[78:79], v[78:79], v[78:79], v[88:89] op_sel_hi:[1,1,0]
	v_mul_f32_e32 v88, v77, v77
	v_pk_fma_f32 v[78:79], v[80:81], v[80:81], v[78:79]
	v_mul_f32_e32 v80, v75, v75
	v_pk_fma_f32 v[74:75], v[74:75], v[74:75], v[80:81] op_sel_hi:[1,1,0]
	v_pk_add_f32 v[78:79], v[94:95], v[78:79] op_sel_hi:[0,1]
	v_pk_fma_f32 v[74:75], v[76:77], v[76:77], v[74:75]
	v_mul_f32_e32 v76, v71, v71
	v_pk_add_f32 v[74:75], v[88:89], v[74:75] op_sel_hi:[0,1]
	v_pk_fma_f32 v[70:71], v[70:71], v[70:71], v[76:77] op_sel_hi:[1,1,0]
	v_pk_add_f32 v[74:75], v[78:79], v[74:75]
	v_mul_f32_e32 v78, v73, v73
	v_pk_fma_f32 v[70:71], v[72:73], v[72:73], v[70:71]
	v_pk_add_f32 v[66:67], v[66:67], v[184:185]
	v_pk_add_f32 v[68:69], v[68:69], v[186:187]
	v_mul_f32_e32 v72, v67, v67
	v_pk_add_f32 v[70:71], v[78:79], v[70:71] op_sel_hi:[0,1]
	global_store_dwordx4 v[92:93], v[66:69], off offset:576
	v_cvt_pk_bf16_f32 v236, v66, v67
	v_pk_add_f32 v[70:71], v[74:75], v[70:71]
	v_pk_fma_f32 v[66:67], v[66:67], v[66:67], v[72:73] op_sel_hi:[1,1,0]
	v_mul_f32_e32 v74, v69, v69
	v_pk_fma_f32 v[66:67], v[68:69], v[68:69], v[66:67]
	v_cvt_pk_bf16_f32 v237, v68, v69
	v_pk_add_f32 v[66:67], v[74:75], v[66:67] op_sel_hi:[0,1]
	v_pk_add_f32 v[66:67], v[70:71], v[66:67]
	v_permlane16_swap_b32_e32 v234, v236
	v_permlane16_swap_b32_e32 v235, v237
	global_store_dwordx4 v[90:91], v[234:237], off offset:256
	v_mov_b32_e32 v67, v66
	s_nop 1
	v_permlane16_swap_b32_e32 v66, v67
	v_add_f32_e32 v66, v66, v67
	v_mov_b32_e32 v67, v66
	s_nop 1
	v_permlane32_swap_b32_e32 v66, v67
	s_and_saveexec_b64 s[24:25], s[4:5]
	s_cbranch_execz .LBB0_759
	v_add_f32_e32 v68, v66, v67
	v_lshl_add_u64 v[66:67], v[82:83], 2, s[12:13]
	global_atomic_add_f32 v[66:67], v68, off
.LBB0_759:
	s_or_b64 exec, exec, s[24:25]
	v_readlane_b32 s64, v239, 0
	v_readlane_b32 s65, v239, 1
	v_readlane_b32 s66, v239, 2
	v_readlane_b32 s67, v239, 3
	s_mov_b64 s[52:53], s[64:65]
	v_add_u32_e32 v66, 0x80, v140
	s_mov_b64 s[54:55], s[66:67]
	v_ashrrev_i32_e32 v67, 31, v66
	v_add_u32_e32 v68, 0xffff8080, v140
	v_cmp_gt_i32_e32 vcc, s57, v66
	v_mov_b32_e32 v70, s55
	v_mov_b32_e32 v71, s53
	v_cndmask_b32_e32 v69, 0, v67, vcc
	v_cndmask_b32_e32 v68, v68, v66, vcc
	v_cndmask_b32_e32 v71, v70, v71, vcc
	v_mov_b32_e32 v70, s54
	v_mov_b32_e32 v72, s52
	v_cndmask_b32_e32 v70, v70, v72, vcc
	v_lshlrev_b64 v[68:69], 12, v[68:69]
	v_lshl_add_u64 v[68:69], v[70:71], 0, v[68:69]
	v_lshl_add_u64 v[72:73], v[68:69], 0, v[142:143]
	global_load_dwordx4 v[68:71], v[72:73], off nt
	global_load_dwordx4 v[176:179], v[72:73], off offset:64 nt
	global_load_dwordx4 v[180:183], v[72:73], off offset:512 nt
	global_load_dwordx4 v[184:187], v[72:73], off offset:576 nt
	v_lshlrev_b64 v[74:75], 11, v[66:67]
	v_lshlrev_b64 v[76:77], 12, v[66:67]
	v_lshl_add_u64 v[74:75], s[10:11], 0, v[74:75]
	v_lshl_add_u64 v[76:77], s[86:87], 0, v[76:77]
	v_lshl_add_u64 v[76:77], v[76:77], 0, v[142:143]
	v_lshl_add_u64 v[74:75], v[138:139], 1, v[74:75]
	v_readlane_b32 s68, v239, 4
	v_readlane_b32 s69, v239, 5
	v_readlane_b32 s70, v239, 6
	v_readlane_b32 s71, v239, 7
	v_readlane_b32 s72, v239, 8
	v_readlane_b32 s73, v239, 9
	v_readlane_b32 s74, v239, 10
	v_readlane_b32 s75, v239, 11
	v_readlane_b32 s76, v239, 12
	v_readlane_b32 s77, v239, 13
	v_readlane_b32 s78, v239, 14
	v_readlane_b32 s79, v239, 15
	s_waitcnt vmcnt(0)
;   __device__ __forceinline__ void operator()(const acc8_t& acc, const pg8::Unit& u, int wr, int wc, int fr, int fq) const {
;     ...
;       for (int m = 0; m < 4; m++) {
;         const int token = (int)EPI_TOKEN(u, ai, m);
;         const float* xr = xrow(p, token);
;         float ss = 0.f;
; #pragma unroll
;         for (int bj = 0; bj < 2; bj++)
; #pragma unroll
;           for (int n = 0; n < 2; n++) {
;             const int f = EPI_COL(u, bj, n);
;             const float4 xv = *(const float4*)(xr + f);
;             const float4 o = make_float4(xv.x + acc[ai][bj][m][n][0], xv.y + acc[ai][bj][m][n][1], xv.z + acc[ai][bj][m][n][2], xv.w + acc[ai][bj][m][n][3]);
;             ss += o.x * o.x + o.y * o.y + o.z * o.z + o.w * o.w;
;             *(float4*)(p.out + O_Y + (size_t)token * 1024 + f) = o;
;             uint2 ob; ob.x = pack2(o.x, o.y); ob.y = pack2(o.z, o.w);
;             *(uint2*)(X1B + (size_t)token * 1024 + f) = ob;
;           }
;         ss = xsum16(ss);
;         ss = xsum32(ss);
;         if (fq == 0) atomicAdd(rss + token, ss);
	v_pk_add_f32 v[62:63], v[62:63], v[68:69]
	v_pk_add_f32 v[64:65], v[64:65], v[70:71]
	v_cvt_pk_bf16_f32 v230, v62, v63
	v_cvt_pk_bf16_f32 v231, v64, v65
	global_store_dwordx4 v[76:77], v[62:65], off
	v_mul_f32_e32 v78, v65, v65
	v_pk_add_f32 v[58:59], v[58:59], v[176:177]
	v_pk_add_f32 v[60:61], v[60:61], v[178:179]
	v_cvt_pk_bf16_f32 v232, v58, v59
	v_cvt_pk_bf16_f32 v233, v60, v61
	global_store_dwordx4 v[76:77], v[58:61], off offset:64
	v_permlane16_swap_b32_e32 v230, v232
	v_permlane16_swap_b32_e32 v231, v233
	global_store_dwordx4 v[74:75], v[230:233], off
	v_pk_add_f32 v[54:55], v[54:55], v[180:181]
	v_pk_add_f32 v[56:57], v[56:57], v[182:183]
	v_cvt_pk_bf16_f32 v234, v54, v55
	v_cvt_pk_bf16_f32 v235, v56, v57
	global_store_dwordx4 v[76:77], v[54:57], off offset:512
	v_mul_f32_e32 v72, v63, v63
	v_pk_fma_f32 v[62:63], v[62:63], v[62:63], v[72:73] op_sel_hi:[1,1,0]
	v_mul_f32_e32 v72, v61, v61
	v_pk_fma_f32 v[62:63], v[64:65], v[64:65], v[62:63]
	v_mul_f32_e32 v64, v59, v59
	v_pk_fma_f32 v[58:59], v[58:59], v[58:59], v[64:65] op_sel_hi:[1,1,0]
	v_pk_add_f32 v[62:63], v[78:79], v[62:63] op_sel_hi:[0,1]
	v_pk_fma_f32 v[58:59], v[60:61], v[60:61], v[58:59]
	v_mul_f32_e32 v60, v55, v55
	v_pk_add_f32 v[58:59], v[72:73], v[58:59] op_sel_hi:[0,1]
	v_pk_fma_f32 v[54:55], v[54:55], v[54:55], v[60:61] op_sel_hi:[1,1,0]
	v_pk_add_f32 v[58:59], v[62:63], v[58:59]
	v_mul_f32_e32 v62, v57, v57
	v_pk_fma_f32 v[54:55], v[56:57], v[56:57], v[54:55]
	v_pk_add_f32 v[50:51], v[50:51], v[184:185]
	v_pk_add_f32 v[52:53], v[52:53], v[186:187]
	v_mul_f32_e32 v56, v51, v51
	v_pk_add_f32 v[54:55], v[62:63], v[54:55] op_sel_hi:[0,1]
	global_store_dwordx4 v[76:77], v[50:53], off offset:576
	v_cvt_pk_bf16_f32 v236, v50, v51
	v_pk_add_f32 v[54:55], v[58:59], v[54:55]
	v_pk_fma_f32 v[50:51], v[50:51], v[50:51], v[56:57] op_sel_hi:[1,1,0]
	v_mul_f32_e32 v58, v53, v53
	v_pk_fma_f32 v[50:51], v[52:53], v[52:53], v[50:51]
	v_cvt_pk_bf16_f32 v237, v52, v53
	v_pk_add_f32 v[50:51], v[58:59], v[50:51] op_sel_hi:[0,1]
	v_pk_add_f32 v[50:51], v[54:55], v[50:51]
	v_permlane16_swap_b32_e32 v234, v236
	v_permlane16_swap_b32_e32 v235, v237
	global_store_dwordx4 v[74:75], v[234:237], off offset:256
	v_mov_b32_e32 v51, v50
	s_nop 1
	v_permlane16_swap_b32_e32 v50, v51
	v_add_f32_e32 v50, v50, v51
	v_mov_b32_e32 v51, v50
	s_nop 1
	v_permlane32_swap_b32_e32 v50, v51
	s_and_saveexec_b64 s[24:25], s[4:5]
	s_cbranch_execz .LBB0_761
	v_add_f32_e32 v52, v50, v51
	v_lshl_add_u64 v[50:51], v[66:67], 2, s[12:13]
	global_atomic_add_f32 v[50:51], v52, off
.LBB0_761:
	s_or_b64 exec, exec, s[24:25]
	v_readlane_b32 s64, v239, 0
	v_readlane_b32 s65, v239, 1
	v_readlane_b32 s66, v239, 2
	v_readlane_b32 s67, v239, 3
	s_mov_b64 s[52:53], s[64:65]
	v_add_u32_e32 v50, 0x90, v140
	s_mov_b64 s[54:55], s[66:67]
	v_ashrrev_i32_e32 v51, 31, v50
	v_add_u32_e32 v52, 0xffff8090, v140
	v_cmp_gt_i32_e32 vcc, s57, v50
	v_mov_b32_e32 v54, s55
	v_mov_b32_e32 v55, s53
	v_cndmask_b32_e32 v53, 0, v51, vcc
	v_cndmask_b32_e32 v52, v52, v50, vcc
	v_cndmask_b32_e32 v55, v54, v55, vcc
	v_mov_b32_e32 v54, s54
	v_mov_b32_e32 v56, s52
	v_cndmask_b32_e32 v54, v54, v56, vcc
	v_lshlrev_b64 v[52:53], 12, v[52:53]
	v_lshl_add_u64 v[52:53], v[54:55], 0, v[52:53]
	v_lshl_add_u64 v[56:57], v[52:53], 0, v[142:143]
	global_load_dwordx4 v[52:55], v[56:57], off nt
	global_load_dwordx4 v[176:179], v[56:57], off offset:64 nt
	global_load_dwordx4 v[180:183], v[56:57], off offset:512 nt
	global_load_dwordx4 v[184:187], v[56:57], off offset:576 nt
	v_lshlrev_b64 v[58:59], 11, v[50:51]
	v_lshlrev_b64 v[60:61], 12, v[50:51]
	v_lshl_add_u64 v[58:59], s[10:11], 0, v[58:59]
	v_lshl_add_u64 v[60:61], s[86:87], 0, v[60:61]
	v_lshl_add_u64 v[60:61], v[60:61], 0, v[142:143]
	v_lshl_add_u64 v[58:59], v[138:139], 1, v[58:59]
	v_readlane_b32 s68, v239, 4
	v_readlane_b32 s69, v239, 5
	v_readlane_b32 s70, v239, 6
	v_readlane_b32 s71, v239, 7
	v_readlane_b32 s72, v239, 8
	v_readlane_b32 s73, v239, 9
	v_readlane_b32 s74, v239, 10
	v_readlane_b32 s75, v239, 11
	v_readlane_b32 s76, v239, 12
	v_readlane_b32 s77, v239, 13
	v_readlane_b32 s78, v239, 14
	v_readlane_b32 s79, v239, 15
	s_waitcnt vmcnt(0)
	v_pk_add_f32 v[46:47], v[46:47], v[52:53]
	v_pk_add_f32 v[48:49], v[48:49], v[54:55]
	v_cvt_pk_bf16_f32 v230, v46, v47
	v_cvt_pk_bf16_f32 v231, v48, v49
	global_store_dwordx4 v[60:61], v[46:49], off
	v_mul_f32_e32 v62, v49, v49
	v_pk_add_f32 v[42:43], v[42:43], v[176:177]
	v_pk_add_f32 v[44:45], v[44:45], v[178:179]
	v_cvt_pk_bf16_f32 v232, v42, v43
	v_cvt_pk_bf16_f32 v233, v44, v45
	global_store_dwordx4 v[60:61], v[42:45], off offset:64
	v_permlane16_swap_b32_e32 v230, v232
	v_permlane16_swap_b32_e32 v231, v233
	global_store_dwordx4 v[58:59], v[230:233], off
	v_pk_add_f32 v[38:39], v[38:39], v[180:181]
	v_pk_add_f32 v[40:41], v[40:41], v[182:183]
	v_cvt_pk_bf16_f32 v234, v38, v39
	v_cvt_pk_bf16_f32 v235, v40, v41
	global_store_dwordx4 v[60:61], v[38:41], off offset:512
	v_mul_f32_e32 v56, v47, v47
	v_pk_fma_f32 v[46:47], v[46:47], v[46:47], v[56:57] op_sel_hi:[1,1,0]
	v_mul_f32_e32 v56, v45, v45
	v_pk_fma_f32 v[46:47], v[48:49], v[48:49], v[46:47]
	v_mul_f32_e32 v48, v43, v43
	v_pk_fma_f32 v[42:43], v[42:43], v[42:43], v[48:49] op_sel_hi:[1,1,0]
	v_pk_add_f32 v[46:47], v[62:63], v[46:47] op_sel_hi:[0,1]
	v_pk_fma_f32 v[42:43], v[44:45], v[44:45], v[42:43]
	v_mul_f32_e32 v44, v39, v39
	v_pk_add_f32 v[42:43], v[56:57], v[42:43] op_sel_hi:[0,1]
	v_pk_fma_f32 v[38:39], v[38:39], v[38:39], v[44:45] op_sel_hi:[1,1,0]
	v_pk_add_f32 v[42:43], v[46:47], v[42:43]
	v_mul_f32_e32 v46, v41, v41
	v_pk_fma_f32 v[38:39], v[40:41], v[40:41], v[38:39]
	v_pk_add_f32 v[34:35], v[34:35], v[184:185]
	v_pk_add_f32 v[36:37], v[36:37], v[186:187]
	v_mul_f32_e32 v40, v35, v35
	v_pk_add_f32 v[38:39], v[46:47], v[38:39] op_sel_hi:[0,1]
	global_store_dwordx4 v[60:61], v[34:37], off offset:576
	v_cvt_pk_bf16_f32 v236, v34, v35
	v_pk_add_f32 v[38:39], v[42:43], v[38:39]
	v_pk_fma_f32 v[34:35], v[34:35], v[34:35], v[40:41] op_sel_hi:[1,1,0]
	v_mul_f32_e32 v42, v37, v37
	v_pk_fma_f32 v[34:35], v[36:37], v[36:37], v[34:35]
	v_cvt_pk_bf16_f32 v237, v36, v37
	v_pk_add_f32 v[34:35], v[42:43], v[34:35] op_sel_hi:[0,1]
	v_pk_add_f32 v[34:35], v[38:39], v[34:35]
	v_permlane16_swap_b32_e32 v234, v236
	v_permlane16_swap_b32_e32 v235, v237
	global_store_dwordx4 v[58:59], v[234:237], off offset:256
	v_mov_b32_e32 v35, v34
	s_nop 1
	v_permlane16_swap_b32_e32 v34, v35
	v_add_f32_e32 v34, v34, v35
	v_mov_b32_e32 v35, v34
	s_nop 1
	v_permlane32_swap_b32_e32 v34, v35
	s_and_saveexec_b64 s[24:25], s[4:5]
	s_cbranch_execz .LBB0_763
	v_add_f32_e32 v36, v34, v35
	v_lshl_add_u64 v[34:35], v[50:51], 2, s[12:13]
	global_atomic_add_f32 v[34:35], v36, off
;   __device__ __forceinline__ void operator()(const acc8_t& acc, const pg8::Unit& u, int wr, int wc, int fr, int fq) const {
;     ...
;       for (int m = 0; m < 4; m++) {
;         const int token = (int)EPI_TOKEN(u, ai, m);
;         const float* xr = xrow(p, token);
;         float ss = 0.f;
; #pragma unroll
;         for (int bj = 0; bj < 2; bj++)
; #pragma unroll
;           for (int n = 0; n < 2; n++) {
;             const int f = EPI_COL(u, bj, n);
;             const float4 xv = *(const float4*)(xr + f);
;             const float4 o = make_float4(xv.x + acc[ai][bj][m][n][0], xv.y + acc[ai][bj][m][n][1], xv.z + acc[ai][bj][m][n][2], xv.w + acc[ai][bj][m][n][3]);
;             ss += o.x * o.x + o.y * o.y + o.z * o.z + o.w * o.w;
;             *(float4*)(p.out + O_Y + (size_t)token * 1024 + f) = o;
;             uint2 ob; ob.x = pack2(o.x, o.y); ob.y = pack2(o.z, o.w);
;             *(uint2*)(X1B + (size_t)token * 1024 + f) = ob;
;           }
;         ss = xsum16(ss);
;         ss = xsum32(ss);
;         if (fq == 0) atomicAdd(rss + token, ss);
.LBB0_763:
	s_or_b64 exec, exec, s[24:25]
	v_readlane_b32 s64, v239, 0
	v_readlane_b32 s65, v239, 1
	v_readlane_b32 s66, v239, 2
	v_readlane_b32 s67, v239, 3
	s_mov_b64 s[52:53], s[64:65]
	v_add_u32_e32 v34, 0xa0, v140
	s_mov_b64 s[54:55], s[66:67]
	v_ashrrev_i32_e32 v35, 31, v34
	v_add_u32_e32 v36, 0xffff80a0, v140
	v_cmp_gt_i32_e32 vcc, s57, v34
	v_mov_b32_e32 v38, s55
	v_mov_b32_e32 v39, s53
	v_cndmask_b32_e32 v37, 0, v35, vcc
	v_cndmask_b32_e32 v36, v36, v34, vcc
	v_cndmask_b32_e32 v39, v38, v39, vcc
	v_mov_b32_e32 v38, s54
	v_mov_b32_e32 v40, s52
	v_cndmask_b32_e32 v38, v38, v40, vcc
	v_lshlrev_b64 v[36:37], 12, v[36:37]
	v_lshl_add_u64 v[36:37], v[38:39], 0, v[36:37]
	v_lshl_add_u64 v[40:41], v[36:37], 0, v[142:143]
	global_load_dwordx4 v[36:39], v[40:41], off nt
	global_load_dwordx4 v[176:179], v[40:41], off offset:64 nt
	global_load_dwordx4 v[180:183], v[40:41], off offset:512 nt
	global_load_dwordx4 v[184:187], v[40:41], off offset:576 nt
	v_lshlrev_b64 v[42:43], 11, v[34:35]
	v_lshlrev_b64 v[44:45], 12, v[34:35]
	v_lshl_add_u64 v[42:43], s[10:11], 0, v[42:43]
	v_lshl_add_u64 v[44:45], s[86:87], 0, v[44:45]
	v_lshl_add_u64 v[44:45], v[44:45], 0, v[142:143]
	v_lshl_add_u64 v[42:43], v[138:139], 1, v[42:43]
	v_readlane_b32 s68, v239, 4
	v_readlane_b32 s69, v239, 5
	v_readlane_b32 s70, v239, 6
	v_readlane_b32 s71, v239, 7
	v_readlane_b32 s72, v239, 8
	v_readlane_b32 s73, v239, 9
	v_readlane_b32 s74, v239, 10
	v_readlane_b32 s75, v239, 11
	v_readlane_b32 s76, v239, 12
	v_readlane_b32 s77, v239, 13
	v_readlane_b32 s78, v239, 14
	v_readlane_b32 s79, v239, 15
	s_waitcnt vmcnt(0)
	v_pk_add_f32 v[30:31], v[30:31], v[36:37]
	v_pk_add_f32 v[32:33], v[32:33], v[38:39]
	v_cvt_pk_bf16_f32 v230, v30, v31
	v_cvt_pk_bf16_f32 v231, v32, v33
	global_store_dwordx4 v[44:45], v[30:33], off
	v_mul_f32_e32 v46, v33, v33
	v_pk_add_f32 v[26:27], v[26:27], v[176:177]
	v_pk_add_f32 v[28:29], v[28:29], v[178:179]
	v_cvt_pk_bf16_f32 v232, v26, v27
	v_cvt_pk_bf16_f32 v233, v28, v29
	global_store_dwordx4 v[44:45], v[26:29], off offset:64
	v_permlane16_swap_b32_e32 v230, v232
	v_permlane16_swap_b32_e32 v231, v233
	global_store_dwordx4 v[42:43], v[230:233], off
	v_pk_add_f32 v[22:23], v[22:23], v[180:181]
	v_pk_add_f32 v[24:25], v[24:25], v[182:183]
	v_cvt_pk_bf16_f32 v234, v22, v23
	v_cvt_pk_bf16_f32 v235, v24, v25
	global_store_dwordx4 v[44:45], v[22:25], off offset:512
	v_mul_f32_e32 v40, v31, v31
	v_pk_fma_f32 v[30:31], v[30:31], v[30:31], v[40:41] op_sel_hi:[1,1,0]
	v_mul_f32_e32 v40, v29, v29
	v_pk_fma_f32 v[30:31], v[32:33], v[32:33], v[30:31]
	v_mul_f32_e32 v32, v27, v27
	v_pk_fma_f32 v[26:27], v[26:27], v[26:27], v[32:33] op_sel_hi:[1,1,0]
	v_pk_add_f32 v[30:31], v[46:47], v[30:31] op_sel_hi:[0,1]
	v_pk_fma_f32 v[26:27], v[28:29], v[28:29], v[26:27]
	v_mul_f32_e32 v28, v23, v23
	v_pk_add_f32 v[26:27], v[40:41], v[26:27] op_sel_hi:[0,1]
	v_pk_fma_f32 v[22:23], v[22:23], v[22:23], v[28:29] op_sel_hi:[1,1,0]
	v_pk_add_f32 v[26:27], v[30:31], v[26:27]
	v_mul_f32_e32 v30, v25, v25
	v_pk_fma_f32 v[22:23], v[24:25], v[24:25], v[22:23]
	v_pk_add_f32 v[18:19], v[18:19], v[184:185]
	v_pk_add_f32 v[20:21], v[20:21], v[186:187]
	v_mul_f32_e32 v24, v19, v19
	v_pk_add_f32 v[22:23], v[30:31], v[22:23] op_sel_hi:[0,1]
	global_store_dwordx4 v[44:45], v[18:21], off offset:576
	v_cvt_pk_bf16_f32 v236, v18, v19
	v_pk_add_f32 v[22:23], v[26:27], v[22:23]
	v_pk_fma_f32 v[18:19], v[18:19], v[18:19], v[24:25] op_sel_hi:[1,1,0]
	v_mul_f32_e32 v26, v21, v21
	v_pk_fma_f32 v[18:19], v[20:21], v[20:21], v[18:19]
	v_cvt_pk_bf16_f32 v237, v20, v21
	v_pk_add_f32 v[18:19], v[26:27], v[18:19] op_sel_hi:[0,1]
	v_pk_add_f32 v[18:19], v[22:23], v[18:19]
	v_permlane16_swap_b32_e32 v234, v236
	v_permlane16_swap_b32_e32 v235, v237
	global_store_dwordx4 v[42:43], v[234:237], off offset:256
	v_mov_b32_e32 v19, v18
	s_nop 1
	v_permlane16_swap_b32_e32 v18, v19
	v_add_f32_e32 v18, v18, v19
	v_mov_b32_e32 v19, v18
	s_nop 1
	v_permlane32_swap_b32_e32 v18, v19
	s_and_saveexec_b64 s[24:25], s[4:5]
	s_cbranch_execz .LBB0_765
	v_add_f32_e32 v20, v18, v19
	v_lshl_add_u64 v[18:19], v[34:35], 2, s[12:13]
	global_atomic_add_f32 v[18:19], v20, off
;   __device__ __forceinline__ void operator()(const acc8_t& acc, const pg8::Unit& u, int wr, int wc, int fr, int fq) const {
;     ...
;       for (int m = 0; m < 4; m++) {
;         const int token = (int)EPI_TOKEN(u, ai, m);
;         const float* xr = xrow(p, token);
;         float ss = 0.f;
; #pragma unroll
;         for (int bj = 0; bj < 2; bj++)
; #pragma unroll
;           for (int n = 0; n < 2; n++) {
;             const int f = EPI_COL(u, bj, n);
;             const float4 xv = *(const float4*)(xr + f);
;             const float4 o = make_float4(xv.x + acc[ai][bj][m][n][0], xv.y + acc[ai][bj][m][n][1], xv.z + acc[ai][bj][m][n][2], xv.w + acc[ai][bj][m][n][3]);
;             ss += o.x * o.x + o.y * o.y + o.z * o.z + o.w * o.w;
;             *(float4*)(p.out + O_Y + (size_t)token * 1024 + f) = o;
;             uint2 ob; ob.x = pack2(o.x, o.y); ob.y = pack2(o.z, o.w);
;             *(uint2*)(X1B + (size_t)token * 1024 + f) = ob;
;           }
;         ss = xsum16(ss);
;         ss = xsum32(ss);
;         if (fq == 0) atomicAdd(rss + token, ss);
.LBB0_765:
	s_or_b64 exec, exec, s[24:25]
	v_readlane_b32 s64, v239, 0
	v_readlane_b32 s65, v239, 1
	v_readlane_b32 s66, v239, 2
	v_readlane_b32 s67, v239, 3
	s_mov_b64 s[52:53], s[64:65]
	v_add_u32_e32 v18, 0xb0, v140
	s_mov_b64 s[54:55], s[66:67]
	v_ashrrev_i32_e32 v19, 31, v18
	v_add_u32_e32 v20, 0xffff80b0, v140
	v_cmp_gt_i32_e32 vcc, s57, v18
	v_mov_b32_e32 v22, s55
	v_mov_b32_e32 v23, s53
	v_cndmask_b32_e32 v21, 0, v19, vcc
	v_cndmask_b32_e32 v20, v20, v18, vcc
	v_cndmask_b32_e32 v23, v22, v23, vcc
	v_mov_b32_e32 v22, s54
	v_mov_b32_e32 v24, s52
	v_cndmask_b32_e32 v22, v22, v24, vcc
	v_lshlrev_b64 v[20:21], 12, v[20:21]
	v_lshl_add_u64 v[20:21], v[22:23], 0, v[20:21]
	v_lshl_add_u64 v[24:25], v[20:21], 0, v[142:143]
	global_load_dwordx4 v[20:23], v[24:25], off nt
	global_load_dwordx4 v[176:179], v[24:25], off offset:64 nt
	global_load_dwordx4 v[180:183], v[24:25], off offset:512 nt
	global_load_dwordx4 v[184:187], v[24:25], off offset:576 nt
	v_lshlrev_b64 v[26:27], 11, v[18:19]
	v_lshlrev_b64 v[28:29], 12, v[18:19]
	v_lshl_add_u64 v[26:27], s[10:11], 0, v[26:27]
	v_lshl_add_u64 v[28:29], s[86:87], 0, v[28:29]
	v_lshl_add_u64 v[28:29], v[28:29], 0, v[142:143]
	v_lshl_add_u64 v[26:27], v[138:139], 1, v[26:27]
	v_readlane_b32 s68, v239, 4
	v_readlane_b32 s69, v239, 5
	v_readlane_b32 s70, v239, 6
	v_readlane_b32 s71, v239, 7
	v_readlane_b32 s72, v239, 8
	v_readlane_b32 s73, v239, 9
	v_readlane_b32 s74, v239, 10
	v_readlane_b32 s75, v239, 11
	v_readlane_b32 s76, v239, 12
	v_readlane_b32 s77, v239, 13
	v_readlane_b32 s78, v239, 14
	v_readlane_b32 s79, v239, 15
	s_waitcnt vmcnt(0)
	v_pk_add_f32 v[14:15], v[14:15], v[20:21]
	v_pk_add_f32 v[16:17], v[16:17], v[22:23]
	v_cvt_pk_bf16_f32 v230, v14, v15
	v_cvt_pk_bf16_f32 v231, v16, v17
	global_store_dwordx4 v[28:29], v[14:17], off
	v_mul_f32_e32 v30, v17, v17
	v_pk_add_f32 v[10:11], v[10:11], v[176:177]
	v_pk_add_f32 v[12:13], v[12:13], v[178:179]
	v_cvt_pk_bf16_f32 v232, v10, v11
	v_cvt_pk_bf16_f32 v233, v12, v13
	global_store_dwordx4 v[28:29], v[10:13], off offset:64
	v_permlane16_swap_b32_e32 v230, v232
	v_permlane16_swap_b32_e32 v231, v233
	global_store_dwordx4 v[26:27], v[230:233], off
	v_pk_add_f32 v[6:7], v[6:7], v[180:181]
	v_pk_add_f32 v[8:9], v[8:9], v[182:183]
	v_cvt_pk_bf16_f32 v234, v6, v7
	v_cvt_pk_bf16_f32 v235, v8, v9
	global_store_dwordx4 v[28:29], v[6:9], off offset:512
	v_mul_f32_e32 v24, v15, v15
	v_pk_fma_f32 v[14:15], v[14:15], v[14:15], v[24:25] op_sel_hi:[1,1,0]
	v_mul_f32_e32 v24, v13, v13
	v_pk_fma_f32 v[14:15], v[16:17], v[16:17], v[14:15]
	v_mul_f32_e32 v16, v11, v11
	v_pk_fma_f32 v[10:11], v[10:11], v[10:11], v[16:17] op_sel_hi:[1,1,0]
	v_pk_add_f32 v[14:15], v[30:31], v[14:15] op_sel_hi:[0,1]
	v_pk_fma_f32 v[10:11], v[12:13], v[12:13], v[10:11]
	v_mul_f32_e32 v12, v7, v7
	v_pk_add_f32 v[10:11], v[24:25], v[10:11] op_sel_hi:[0,1]
	v_pk_fma_f32 v[6:7], v[6:7], v[6:7], v[12:13] op_sel_hi:[1,1,0]
	v_pk_add_f32 v[10:11], v[14:15], v[10:11]
	v_mul_f32_e32 v14, v9, v9
	v_pk_fma_f32 v[6:7], v[8:9], v[8:9], v[6:7]
	v_pk_add_f32 v[2:3], v[2:3], v[184:185]
	v_pk_add_f32 v[4:5], v[4:5], v[186:187]
	v_mul_f32_e32 v8, v3, v3
	v_pk_add_f32 v[6:7], v[14:15], v[6:7] op_sel_hi:[0,1]
	global_store_dwordx4 v[28:29], v[2:5], off offset:576
	v_cvt_pk_bf16_f32 v236, v2, v3
	v_pk_add_f32 v[6:7], v[10:11], v[6:7]
	v_pk_fma_f32 v[2:3], v[2:3], v[2:3], v[8:9] op_sel_hi:[1,1,0]
	v_mul_f32_e32 v10, v5, v5
	v_pk_fma_f32 v[2:3], v[4:5], v[4:5], v[2:3]
	v_cvt_pk_bf16_f32 v237, v4, v5
	v_pk_add_f32 v[2:3], v[10:11], v[2:3] op_sel_hi:[0,1]
	v_pk_add_f32 v[2:3], v[6:7], v[2:3]
	v_permlane16_swap_b32_e32 v234, v236
	v_permlane16_swap_b32_e32 v235, v237
	global_store_dwordx4 v[26:27], v[234:237], off offset:256
	v_mov_b32_e32 v3, v2
	s_nop 1
	v_permlane16_swap_b32_e32 v2, v3
	v_add_f32_e32 v2, v2, v3
	v_mov_b32_e32 v3, v2
	s_nop 1
	v_permlane32_swap_b32_e32 v2, v3
	s_and_saveexec_b64 s[24:25], s[4:5]
	s_cbranch_execz .LBB0_743
	v_add_f32_e32 v4, v2, v3
	v_lshl_add_u64 v[2:3], v[18:19], 2, s[12:13]
	global_atomic_add_f32 v[2:3], v4, off
	s_branch .LBB0_743
